# ret_u: V staging loads batched; per-head decay constants computed on the first item only
# speedup vs baseline: 1.0042x; 1.0024x over previous
.LBB0_333:
	s_bfe_u32 s11, s9, 0x20004
	s_lshl_b32 s6, s11, 2
	v_mov_b32_e32 v35, v230
	v_mov_b32_e32 v0, s6
	global_load_dword v2, v0, s[56:57]
	s_and_b32 s10, s9, 15
	global_load_dword v0, v0, s[56:57] offset:16
	s_and_b32 s6, s8, 0xfffff800
	s_lshl_b32 s7, s10, 7
	s_or_b32 s13, s6, s7
	v_and_b32_e32 v22, 3, v35
	s_lshl_b32 s6, s11, 6
	s_lshr_b32 s12, s9, 4
	s_bfe_u32 s7, s12, 0x10001
	s_or_b32 s7, s7, 20
	v_bfe_u32 v36, v35, 5, 1
	v_ashrrev_i32_e32 v34, 8, v35
	v_lshl_add_u32 v37, v34, 14, 0
	s_waitcnt vmcnt(0)
	s_cmp_lg_u32 s9, s48
	s_cbranch_scc1 .Lretu_dskip
	v_mul_f32_e32 v3, 0xbfb8aa3b, v2
	v_fma_f32 v4, v2, s61, -v3
	v_rndne_f32_e32 v5, v3
	v_fmac_f32_e32 v4, 0xb2a5705f, v2
	v_sub_f32_e32 v3, v3, v5
	v_add_f32_e32 v3, v3, v4
	v_exp_f32_e32 v3, v3
	v_cvt_i32_f32_e32 v4, v5
	v_cmp_nlt_f32_e32 vcc, s74, v2
	v_ldexp_f32 v3, v3, v4
	s_nop 0
	v_cndmask_b32_e32 v3, 0, v3, vcc
	v_cmp_ngt_f32_e32 vcc, s75, v2
	s_nop 1
	v_cndmask_b32_e32 v18, v235, v3, vcc
	v_add_f32_e32 v4, 1.0, v18
	v_add_f32_e32 v2, -1.0, v4
	v_sub_f32_e32 v3, v2, v4
	v_add_f32_e32 v3, 1.0, v3
	v_sub_f32_e32 v2, v18, v2
	v_add_f32_e32 v5, v2, v3
	v_frexp_mant_f32_e32 v2, v4
	v_cmp_gt_f32_e32 vcc, s77, v2
	v_cvt_f64_f32_e32 v[2:3], v4
	v_frexp_exp_i32_f64_e32 v2, v[2:3]
	v_subbrev_co_u32_e32 v10, vcc, 0, v2, vcc
	v_sub_u32_e32 v2, 0, v10
	v_ldexp_f32 v3, v4, v2
	v_add_f32_e32 v4, -1.0, v3
	v_add_f32_e32 v6, 1.0, v3
	v_ldexp_f32 v2, v5, v2
	v_add_f32_e32 v5, 1.0, v4
	v_add_f32_e32 v7, -1.0, v6
	v_sub_f32_e32 v5, v3, v5
	v_sub_f32_e32 v3, v3, v7
	v_add_f32_e32 v5, v2, v5
	v_add_f32_e32 v2, v2, v3
	v_add_f32_e32 v11, v6, v2
	v_rcp_f32_e32 v13, v11
	v_sub_f32_e32 v3, v6, v11
	v_add_f32_e32 v12, v2, v3
	v_add_f32_e32 v3, v4, v5
	v_mul_f32_e32 v15, v3, v13
	v_sub_f32_e32 v2, v4, v3
	v_mul_f32_e32 v4, v11, v15
	v_fma_f32 v6, v15, v11, -v4
	v_fmac_f32_e32 v6, v15, v12
	v_add_f32_e32 v14, v5, v2
	v_add_f32_e32 v2, v4, v6
	v_sub_f32_e32 v5, v3, v2
	v_pk_add_f32 v[8:9], v[2:3], v[4:5] neg_lo:[0,1] neg_hi:[0,1]
	v_mov_b32_e32 v7, v2
	v_pk_add_f32 v[2:3], v[8:9], v[6:7] neg_lo:[0,1] neg_hi:[0,1]
	v_cmp_neq_f32_e32 vcc, s76, v18
	v_add_f32_e32 v3, v14, v3
	v_add_f32_e32 v2, v2, v3
	v_add_f32_e32 v3, v5, v2
	v_mul_f32_e32 v14, v13, v3
	v_mul_f32_e32 v4, v11, v14
	v_fma_f32 v6, v14, v11, -v4
	v_fmac_f32_e32 v6, v14, v12
	v_sub_f32_e32 v5, v5, v3
	v_add_f32_e32 v11, v2, v5
	v_add_f32_e32 v2, v4, v6
	v_sub_f32_e32 v5, v3, v2
	v_pk_add_f32 v[8:9], v[2:3], v[4:5] neg_lo:[0,1] neg_hi:[0,1]
	v_mov_b32_e32 v7, v2
	v_pk_add_f32 v[2:3], v[8:9], v[6:7] neg_lo:[0,1] neg_hi:[0,1]
	s_nop 0
	v_add_f32_e32 v3, v11, v3
	v_add_f32_e32 v2, v2, v3
	v_add_f32_e32 v3, v15, v14
	v_add_f32_e32 v2, v5, v2
	v_sub_f32_e32 v4, v3, v15
	v_mul_f32_e32 v2, v13, v2
	v_sub_f32_e32 v4, v14, v4
	v_add_f32_e32 v4, v4, v2
	v_add_f32_e32 v6, v3, v4
	v_mul_f32_e32 v7, v6, v6
	v_fmamk_f32 v2, v7, 0x3e9b6dac, v232
	v_fmaak_f32 v179, v7, v2, 0x3f2aaada
	v_cvt_f32_i32_e32 v2, v10
	v_sub_f32_e32 v3, v6, v3
	v_sub_f32_e32 v3, v4, v3
	v_ldexp_f32 v8, v3, 1
	v_mul_f32_e32 v3, v6, v7
	v_ldexp_f32 v5, v6, 1
	v_pk_mul_f32 v[6:7], v[2:3], v[178:179]
	s_nop 0
	v_fma_f32 v4, v2, s86, -v6
	v_fmac_f32_e32 v4, 0xb102e308, v2
	v_pk_add_f32 v[2:3], v[6:7], v[4:5]
	s_nop 0
	v_sub_f32_e32 v5, v3, v5
	v_sub_f32_e32 v5, v7, v5
	v_add_f32_e32 v9, v8, v5
	v_mov_b32_e32 v8, v6
	v_pk_add_f32 v[6:7], v[2:3], v[6:7] neg_lo:[0,1] neg_hi:[0,1]
	v_pk_add_f32 v[10:11], v[2:3], v[8:9]
	v_mov_b32_e32 v5, v2
	v_mov_b32_e32 v7, v11
	v_pk_add_f32 v[12:13], v[4:5], v[6:7] neg_lo:[0,1] neg_hi:[0,1]
	v_pk_add_f32 v[4:5], v[4:5], v[6:7]
	v_mov_b32_e32 v16, v3
	v_pk_add_f32 v[6:7], v[4:5], v[2:3] op_sel:[1,0] op_sel_hi:[0,1] neg_lo:[0,1] neg_hi:[0,1]
	v_pk_add_f32 v[14:15], v[10:11], v[6:7] op_sel_hi:[1,0] neg_lo:[0,1] neg_hi:[0,1]
	v_mov_b32_e32 v10, v11
	v_mov_b32_e32 v11, v5
	v_mov_b32_e32 v17, v6
	v_pk_add_f32 v[6:7], v[10:11], v[16:17] neg_lo:[0,1] neg_hi:[0,1]
	v_mov_b32_e32 v8, v9
	v_mov_b32_e32 v9, v2
	v_pk_add_f32 v[2:3], v[8:9], v[6:7] neg_lo:[0,1] neg_hi:[0,1]
	v_mov_b32_e32 v14, v12
	v_pk_add_f32 v[6:7], v[14:15], v[2:3]
	v_mov_b32_e32 v13, v5
	v_pk_add_f32 v[8:9], v[6:7], v[6:7] op_sel:[0,1] op_sel_hi:[1,0]
	s_nop 0
	v_pk_add_f32 v[4:5], v[4:5], v[8:9] op_sel:[1,0] op_sel_hi:[0,1]
	v_mov_b32_e32 v7, v4
	v_pk_add_f32 v[10:11], v[6:7], v[12:13] neg_lo:[0,1] neg_hi:[0,1]
	v_mov_b32_e32 v3, v8
	v_sub_f32_e32 v5, v6, v10
	v_pk_add_f32 v[2:3], v[2:3], v[10:11] neg_lo:[0,1] neg_hi:[0,1]
	v_sub_f32_e32 v5, v12, v5
	v_add_f32_e32 v2, v2, v5
	v_add_f32_e32 v2, v2, v3
	v_mul_f32_e32 v3, 0xbfb8aa3b, v0
	v_add_f32_e32 v2, v4, v2
	v_fma_f32 v4, v0, s61, -v3
	v_rndne_f32_e32 v5, v3
	v_fmac_f32_e32 v4, 0xb2a5705f, v0
	v_sub_f32_e32 v3, v3, v5
	v_add_f32_e32 v3, v3, v4
	v_exp_f32_e32 v3, v3
	v_cvt_i32_f32_e32 v4, v5
	v_cndmask_b32_e32 v2, v235, v2, vcc
	v_cmp_lt_f32_e64 vcc, |v18|, s87
	v_ldexp_f32 v3, v3, v4
	s_nop 0
	v_cndmask_b32_e32 v2, v2, v18, vcc
	v_cmp_nlt_f32_e32 vcc, s74, v0
	v_mul_f32_e32 v2, 0xbfb8aa3b, v2
	s_nop 0
	v_cndmask_b32_e32 v3, 0, v3, vcc
	v_cmp_ngt_f32_e32 vcc, s75, v0
	s_nop 1
	v_cndmask_b32_e32 v0, v235, v3, vcc
	v_add_f32_e32 v3, 1.0, v0
	v_add_f32_e32 v4, -1.0, v3
	v_sub_f32_e32 v5, v4, v3
	v_add_f32_e32 v5, 1.0, v5
	v_sub_f32_e32 v4, v0, v4
	v_add_f32_e32 v6, v4, v5
	v_frexp_mant_f32_e32 v4, v3
	v_cmp_gt_f32_e32 vcc, s77, v4
	v_cvt_f64_f32_e32 v[4:5], v3
	v_frexp_exp_i32_f64_e32 v4, v[4:5]
	v_subbrev_co_u32_e32 v12, vcc, 0, v4, vcc
	v_sub_u32_e32 v4, 0, v12
	v_ldexp_f32 v3, v3, v4
	v_ldexp_f32 v4, v6, v4
	v_add_f32_e32 v6, -1.0, v3
	v_add_f32_e32 v5, 1.0, v6
	v_sub_f32_e32 v5, v3, v5
	v_add_f32_e32 v7, v4, v5
	v_add_f32_e32 v5, 1.0, v3
	v_add_f32_e32 v8, -1.0, v5
	v_sub_f32_e32 v3, v3, v8
	v_add_f32_e32 v3, v4, v3
	v_add_f32_e32 v13, v5, v3
	v_rcp_f32_e32 v14, v13
	v_sub_f32_e32 v4, v5, v13
	v_add_f32_e32 v5, v6, v7
	v_add_f32_e32 v3, v3, v4
	v_mul_f32_e32 v16, v5, v14
	v_sub_f32_e32 v4, v6, v5
	v_mul_f32_e32 v6, v13, v16
	v_fma_f32 v8, v16, v13, -v6
	v_fmac_f32_e32 v8, v16, v3
	v_add_f32_e32 v15, v7, v4
	v_add_f32_e32 v4, v6, v8
	v_sub_f32_e32 v7, v5, v4
	v_pk_add_f32 v[10:11], v[4:5], v[6:7] neg_lo:[0,1] neg_hi:[0,1]
	v_mov_b32_e32 v9, v4
	v_pk_add_f32 v[4:5], v[10:11], v[8:9] neg_lo:[0,1] neg_hi:[0,1]
	v_cmp_neq_f32_e32 vcc, s76, v0
	v_add_f32_e32 v5, v15, v5
	v_add_f32_e32 v4, v4, v5
	v_add_f32_e32 v5, v7, v4
	v_mul_f32_e32 v15, v14, v5
	v_mul_f32_e32 v6, v13, v15
	v_fma_f32 v8, v15, v13, -v6
	v_fmac_f32_e32 v8, v15, v3
	v_sub_f32_e32 v3, v7, v5
	v_add_f32_e32 v3, v4, v3
	v_add_f32_e32 v4, v6, v8
	v_sub_f32_e32 v7, v5, v4
	v_pk_add_f32 v[10:11], v[4:5], v[6:7] neg_lo:[0,1] neg_hi:[0,1]
	v_mov_b32_e32 v9, v4
	v_pk_add_f32 v[4:5], v[10:11], v[8:9] neg_lo:[0,1] neg_hi:[0,1]
	s_nop 0
	v_add_f32_e32 v3, v3, v5
	v_add_f32_e32 v3, v4, v3
	v_add_f32_e32 v5, v16, v15
	v_add_f32_e32 v3, v7, v3
	v_sub_f32_e32 v4, v5, v16
	v_mul_f32_e32 v3, v14, v3
	v_sub_f32_e32 v4, v15, v4
	v_add_f32_e32 v3, v4, v3
	v_add_f32_e32 v6, v5, v3
	v_mul_f32_e32 v8, v6, v6
	v_fmamk_f32 v4, v8, 0x3e9b6dac, v232
	v_fmaak_f32 v179, v8, v4, 0x3f2aaada
	v_cvt_f32_i32_e32 v4, v12
	v_sub_f32_e32 v5, v6, v5
	v_sub_f32_e32 v3, v3, v5
	v_mul_f32_e32 v5, v6, v8
	v_pk_mul_f32 v[8:9], v[4:5], v[178:179]
	v_ldexp_f32 v7, v6, 1
	v_fma_f32 v6, v4, s86, -v8
	v_fmac_f32_e32 v6, 0xb102e308, v4
	v_pk_add_f32 v[4:5], v[8:9], v[6:7]
	v_ldexp_f32 v3, v3, 1
	v_sub_f32_e32 v7, v5, v7
	v_sub_f32_e32 v7, v9, v7
	v_add_f32_e32 v11, v3, v7
	v_mov_b32_e32 v10, v8
	v_pk_add_f32 v[8:9], v[4:5], v[8:9] neg_lo:[0,1] neg_hi:[0,1]
	v_pk_add_f32 v[12:13], v[4:5], v[10:11]
	v_mov_b32_e32 v7, v4
	v_mov_b32_e32 v9, v13
	v_pk_add_f32 v[14:15], v[6:7], v[8:9] neg_lo:[0,1] neg_hi:[0,1]
	v_pk_add_f32 v[6:7], v[6:7], v[8:9]
	v_mov_b32_e32 v18, v5
	v_pk_add_f32 v[8:9], v[6:7], v[4:5] op_sel:[1,0] op_sel_hi:[0,1] neg_lo:[0,1] neg_hi:[0,1]
	v_pk_add_f32 v[16:17], v[12:13], v[8:9] op_sel_hi:[1,0] neg_lo:[0,1] neg_hi:[0,1]
	v_mov_b32_e32 v12, v13
	v_mov_b32_e32 v13, v7
	v_mov_b32_e32 v19, v8
	v_pk_add_f32 v[8:9], v[12:13], v[18:19] neg_lo:[0,1] neg_hi:[0,1]
	v_mov_b32_e32 v10, v11
	v_mov_b32_e32 v11, v4
	v_pk_add_f32 v[4:5], v[10:11], v[8:9] neg_lo:[0,1] neg_hi:[0,1]
	v_mov_b32_e32 v16, v14
	v_pk_add_f32 v[8:9], v[16:17], v[4:5]
	v_mov_b32_e32 v15, v7
	v_pk_add_f32 v[10:11], v[8:9], v[8:9] op_sel:[0,1] op_sel_hi:[1,0]
	s_nop 0
	v_pk_add_f32 v[6:7], v[6:7], v[10:11] op_sel:[1,0] op_sel_hi:[0,1]
	v_mov_b32_e32 v9, v6
	v_pk_add_f32 v[12:13], v[8:9], v[14:15] neg_lo:[0,1] neg_hi:[0,1]
	v_mov_b32_e32 v5, v10
	v_sub_f32_e32 v3, v8, v12
	v_pk_add_f32 v[4:5], v[4:5], v[12:13] neg_lo:[0,1] neg_hi:[0,1]
	v_sub_f32_e32 v3, v14, v3
	v_add_f32_e32 v3, v4, v3
	v_add_f32_e32 v3, v3, v5
	v_add_f32_e32 v3, v6, v3
	v_cndmask_b32_e32 v3, v235, v3, vcc
	v_cmp_lt_f32_e64 vcc, |v0|, s87
	v_ashrrev_i32_e32 v13, 2, v35
	v_lshl_or_b32 v6, v22, 4, s6
	v_cndmask_b32_e32 v0, v3, v0, vcc
	v_mul_f32_e32 v3, 0xbfb8aa3b, v0
	v_mov_b32_e32 v180, v2
	v_mov_b32_e32 v181, v3
	s_branch .Lretu_djoin
.Lretu_dskip:
	v_ashrrev_i32_e32 v13, 2, v35
	v_lshl_or_b32 v6, v22, 4, s6
	v_mov_b32_e32 v2, v180
	v_mov_b32_e32 v3, v181
.Lretu_djoin:
	v_add_u32_e32 v0, s13, v13
	v_lshrrev_b32_e32 v4, 8, v0
	v_mul_i32_i24_e32 v4, 38, v4
	v_ashrrev_i32_e32 v5, 31, v4
	v_lshlrev_b32_e32 v0, 8, v0
	v_lshlrev_b64 v[4:5], 17, v[4:5]
	v_and_or_b32 v0, v0, s60, v6
	v_lshl_add_u64 v[4:5], s[0:1], 0, v[4:5]
	v_lshlrev_b32_e32 v0, 1, v0
	v_lshl_add_u64 v[4:5], v[4:5], 0, v[0:1]
	v_lshl_add_u64 v[8:9], v[4:5], 0, s[30:31]
	v_add_co_u32_e32 v4, vcc, s96, v4
	v_sub_u32_e32 v0, 0x7f, v13
	s_nop 0
	v_addc_co_u32_e32 v5, vcc, 0, v5, vcc
	global_load_dwordx4 v[4:7], v[4:5], off
	s_nop 0
	global_load_dwordx4 v[8:11], v[8:9], off offset:16
	v_cvt_f32_i32_e32 v0, v0
	s_lshl_b32 s6, s9, 3
	s_and_b32 s6, s6, 0x80
	v_mul_f32_e32 v12, v2, v0
	v_cmp_gt_f32_e32 vcc, s97, v12
	s_waitcnt vmcnt(0)
	v_lshlrev_b32_e32 v14, 16, v4
	v_cndmask_b32_e32 v12, 0, v233, vcc
	v_fmac_f32_e32 v12, v2, v0
	v_exp_f32_e32 v0, v12
	v_cndmask_b32_e32 v2, 0, v236, vcc
	v_and_b32_e32 v15, 0xffff0000, v4
	v_lshlrev_b32_e32 v16, 16, v5
	v_ldexp_f32 v0, v0, v2
	v_cvt_f32_i32_e32 v2, v13
	v_and_b32_e32 v17, 0xffff0000, v5
	v_pk_mul_f32 v[4:5], v[0:1], v[16:17] op_sel_hi:[0,1]
	v_lshlrev_b32_e32 v18, 16, v6
	v_mul_f32_e32 v12, v3, v2
	v_cmp_gt_f32_e32 vcc, s97, v12
	v_and_b32_e32 v19, 0xffff0000, v6
	v_lshlrev_b32_e32 v6, 16, v7
	v_cndmask_b32_e32 v12, 0, v233, vcc
	v_fmac_f32_e32 v12, v3, v2
	v_exp_f32_e32 v2, v12
	v_cndmask_b32_e32 v3, 0, v236, vcc
	v_and_b32_e32 v7, 0xffff0000, v7
	v_pk_mul_f32 v[20:21], v[0:1], v[6:7] op_sel_hi:[0,1]
	v_ldexp_f32 v12, v2, v3
	v_pk_mul_f32 v[2:3], v[0:1], v[14:15] op_sel_hi:[0,1]
	v_cvt_pk_bf16_f32 v2, v2, v3
	v_cvt_pk_bf16_f32 v3, v4, v5
	v_pk_mul_f32 v[4:5], v[0:1], v[18:19] op_sel_hi:[0,1]
	v_cvt_pk_bf16_f32 v4, v4, v5
	v_cvt_pk_bf16_f32 v5, v20, v21
	v_lshlrev_b32_e32 v13, 7, v13
	v_lshlrev_b32_e32 v20, 5, v22
	v_add3_u32 v13, 0, v13, v20
	v_lshlrev_b32_e32 v20, 16, v8
	v_and_b32_e32 v21, 0xffff0000, v8
	v_lshlrev_b32_e32 v8, 16, v9
	v_and_b32_e32 v9, 0xffff0000, v9
	ds_write_b128 v13, v[2:5]
	v_pk_mul_f32 v[2:3], v[0:1], v[20:21] op_sel_hi:[0,1]
	v_pk_mul_f32 v[4:5], v[0:1], v[8:9] op_sel_hi:[0,1]
	v_lshlrev_b32_e32 v22, 16, v10
	v_and_b32_e32 v23, 0xffff0000, v10
	v_lshlrev_b32_e32 v10, 16, v11
	v_and_b32_e32 v11, 0xffff0000, v11
	v_cvt_pk_bf16_f32 v2, v2, v3
	v_cvt_pk_bf16_f32 v3, v4, v5
	v_pk_mul_f32 v[4:5], v[0:1], v[22:23] op_sel_hi:[0,1]
	v_pk_mul_f32 v[24:25], v[0:1], v[10:11] op_sel_hi:[0,1]
	v_cvt_pk_bf16_f32 v4, v4, v5
	v_cvt_pk_bf16_f32 v5, v24, v25
	ds_write_b128 v13, v[2:5] offset:16
	v_pk_mul_f32 v[2:3], v[12:13], v[14:15] op_sel_hi:[0,1]
	v_pk_mul_f32 v[4:5], v[12:13], v[16:17] op_sel_hi:[0,1]
	v_cvt_pk_bf16_f32 v2, v2, v3
	v_cvt_pk_bf16_f32 v3, v4, v5
	v_pk_mul_f32 v[4:5], v[12:13], v[18:19] op_sel_hi:[0,1]
	v_pk_mul_f32 v[6:7], v[12:13], v[6:7] op_sel_hi:[0,1]
	v_cvt_pk_bf16_f32 v4, v4, v5
	v_cvt_pk_bf16_f32 v5, v6, v7
	ds_write_b128 v13, v[2:5] offset:16384
	v_pk_mul_f32 v[2:3], v[12:13], v[20:21] op_sel_hi:[0,1]
	v_pk_mul_f32 v[4:5], v[12:13], v[8:9] op_sel_hi:[0,1]
	v_cvt_pk_bf16_f32 v2, v2, v3
	v_cvt_pk_bf16_f32 v3, v4, v5
	v_pk_mul_f32 v[4:5], v[12:13], v[22:23] op_sel_hi:[0,1]
	v_pk_mul_f32 v[6:7], v[12:13], v[10:11] op_sel_hi:[0,1]
	v_and_b32_e32 v0, 15, v35
	v_ashrrev_i32_e32 v8, 4, v35
	v_cvt_pk_bf16_f32 v4, v4, v5
	v_cvt_pk_bf16_f32 v5, v6, v7
	v_lshl_or_b32 v6, v0, 3, s6
	v_lshl_add_u32 v7, v0, 4, 0
	v_add_u32_e32 v0, s13, v8
	ds_write_b128 v13, v[2:5] offset:16400
	v_lshrrev_b32_e32 v2, 8, v0
	v_mad_i32_i24 v2, v2, 38, s7
	v_ashrrev_i32_e32 v3, 31, v2
	v_lshlrev_b32_e32 v0, 8, v0
	v_and_or_b32 v0, v0, s60, v6
	v_lshlrev_b64 v[2:3], 17, v[2:3]
	v_lshl_add_u64 v[2:3], s[0:1], 0, v[2:3]
	v_lshlrev_b32_e32 v0, 1, v0
	v_lshl_add_u64 v[2:3], v[2:3], 0, v[0:1]
	global_load_dwordx4 v[184:187], v[2:3], off
	v_lshl_add_u32 v200, v8, 8, v7
	s_and_b32 s6, s9, 0xffffffc0
	v_add_u32_e32 v0, 0x200, v35
	v_ashrrev_i32_e32 v8, 4, v0
	v_add_u32_e32 v0, s13, v8
	v_lshrrev_b32_e32 v2, 8, v0
	v_mad_i32_i24 v2, v2, 38, s7
	v_ashrrev_i32_e32 v3, 31, v2
	v_lshlrev_b32_e32 v0, 8, v0
	v_and_or_b32 v0, v0, s60, v6
	v_lshlrev_b64 v[2:3], 17, v[2:3]
	v_lshl_add_u64 v[2:3], s[0:1], 0, v[2:3]
	v_lshlrev_b32_e32 v0, 1, v0
	v_lshl_add_u64 v[2:3], v[2:3], 0, v[0:1]
	global_load_dwordx4 v[188:191], v[2:3], off
	v_lshl_add_u32 v201, v8, 8, v7
	v_add_u32_e32 v0, 0x400, v35
	v_ashrrev_i32_e32 v8, 4, v0
	v_add_u32_e32 v0, s13, v8
	v_lshrrev_b32_e32 v2, 8, v0
	v_mad_i32_i24 v2, v2, 38, s7
	v_ashrrev_i32_e32 v3, 31, v2
	v_lshlrev_b32_e32 v0, 8, v0
	v_and_or_b32 v0, v0, s60, v6
	v_lshlrev_b64 v[2:3], 17, v[2:3]
	v_lshl_add_u64 v[2:3], s[0:1], 0, v[2:3]
	v_lshlrev_b32_e32 v0, 1, v0
	v_lshl_add_u64 v[2:3], v[2:3], 0, v[0:1]
	global_load_dwordx4 v[192:195], v[2:3], off
	v_lshl_add_u32 v202, v8, 8, v7
	v_add_u32_e32 v0, 0x600, v35
	v_ashrrev_i32_e32 v8, 4, v0
	v_add_u32_e32 v0, s13, v8
	v_lshrrev_b32_e32 v2, 8, v0
	v_mad_i32_i24 v2, v2, 38, s7
	v_ashrrev_i32_e32 v3, 31, v2
	v_lshlrev_b32_e32 v0, 8, v0
	v_and_or_b32 v0, v0, s60, v6
	v_lshlrev_b64 v[2:3], 17, v[2:3]
	v_lshl_add_u64 v[2:3], s[0:1], 0, v[2:3]
	v_lshlrev_b32_e32 v0, 1, v0
	v_lshl_add_u64 v[2:3], v[2:3], 0, v[0:1]
	global_load_dwordx4 v[196:199], v[2:3], off
	v_lshl_add_u32 v203, v8, 8, v7
	s_lshl_b32 s7, s11, 4
	s_or_b32 s6, s7, s6
	s_or_b32 s6, s6, s10
	s_ashr_i32 s7, s6, 31
	s_lshl_b64 s[6:7], s[6:7], 15
	s_add_u32 s6, s2, s6
	s_addc_u32 s7, s3, s7
	s_add_i32 s9, s9, s92
	s_add_i32 s8, s8, s29
	s_cmpk_gt_i32 s9, 0x3ff
	s_waitcnt vmcnt(3)
	ds_write_b128 v200, v[184:187] offset:32768
	s_waitcnt vmcnt(2)
	ds_write_b128 v201, v[188:191] offset:32768
	s_waitcnt vmcnt(1)
	ds_write_b128 v202, v[192:195] offset:32768
	s_waitcnt vmcnt(0)
	ds_write_b128 v203, v[196:199] offset:32768
	v_bfe_u32 v0, v35, 2, 2
	v_lshl_or_b32 v46, v36, 3, v0
	v_lshrrev_b32_e32 v0, 1, v35
	v_lshlrev_b32_e32 v3, 2, v35
	v_and_b32_e32 v2, 16, v35
	v_and_b32_e32 v0, 0x60, v0
	v_and_b32_e32 v3, 12, v3
	v_or3_b32 v4, v2, v0, v3
	v_or_b32_e32 v2, v3, v2
	v_lshl_add_u32 v47, v4, 1, 0
	v_lshlrev_b32_e32 v48, 1, v2
	v_lshlrev_b32_e32 v6, 7, v46
	v_lshl_add_u32 v4, v46, 8, v47
	v_add3_u32 v10, v37, v6, v48
	s_waitcnt lgkmcnt(0)
	s_barrier
	ds_read_b64_tr_b16 v[2:3], v4 offset:32768
	ds_read_b64_tr_b16 v[4:5], v4 offset:33792
	ds_read_b64_tr_b16 v[6:7], v10
	ds_read_b64_tr_b16 v[8:9], v10 offset:512
	s_waitcnt lgkmcnt(0)
	v_mfma_f32_32x32x16_bf16 v[18:33], v[6:9], v[2:5], 0
	ds_read_b64_tr_b16 v[6:7], v10 offset:64
	ds_read_b64_tr_b16 v[8:9], v10 offset:576
	v_or_b32_e32 v42, 16, v46
	v_lshl_add_u32 v40, v42, 8, v47
	v_lshlrev_b32_e32 v42, 7, v42
	v_add3_u32 v49, v37, v42, v48
	ds_read_b64_tr_b16 v[38:39], v40 offset:32768
	ds_read_b64_tr_b16 v[40:41], v40 offset:33792
	ds_read_b64_tr_b16 v[42:43], v49
	ds_read_b64_tr_b16 v[44:45], v49 offset:512
	s_waitcnt lgkmcnt(4)
	v_mfma_f32_32x32x16_bf16 v[2:17], v[6:9], v[2:5], 0
	v_lshlrev_b32_e32 v36, 9, v36
	s_waitcnt lgkmcnt(0)
	v_mfma_f32_32x32x16_bf16 v[18:33], v[42:45], v[38:41], v[18:33]
	ds_read_b64_tr_b16 v[42:43], v49 offset:64
	ds_read_b64_tr_b16 v[44:45], v49 offset:576
	s_waitcnt lgkmcnt(0)
	v_mfma_f32_32x32x16_bf16 v[2:17], v[42:45], v[38:41], v[2:17]
	v_or_b32_e32 v42, 32, v46
	v_lshl_add_u32 v40, v42, 8, v47
	v_lshlrev_b32_e32 v42, 7, v42
	v_add3_u32 v49, v37, v42, v48
	ds_read_b64_tr_b16 v[38:39], v40 offset:32768
	ds_read_b64_tr_b16 v[40:41], v40 offset:33792
	ds_read_b64_tr_b16 v[42:43], v49
	ds_read_b64_tr_b16 v[44:45], v49 offset:512
	s_waitcnt lgkmcnt(0)
	v_mfma_f32_32x32x16_bf16 v[18:33], v[42:45], v[38:41], v[18:33]
	ds_read_b64_tr_b16 v[42:43], v49 offset:64
	ds_read_b64_tr_b16 v[44:45], v49 offset:576
	s_waitcnt lgkmcnt(0)
	v_mfma_f32_32x32x16_bf16 v[2:17], v[42:45], v[38:41], v[2:17]
	v_or_b32_e32 v42, 48, v46
	v_lshl_add_u32 v40, v42, 8, v47
	v_lshlrev_b32_e32 v42, 7, v42
	v_add3_u32 v49, v37, v42, v48
	ds_read_b64_tr_b16 v[38:39], v40 offset:32768
	ds_read_b64_tr_b16 v[40:41], v40 offset:33792
	ds_read_b64_tr_b16 v[42:43], v49
	ds_read_b64_tr_b16 v[44:45], v49 offset:512
	s_waitcnt lgkmcnt(0)
	v_mfma_f32_32x32x16_bf16 v[18:33], v[42:45], v[38:41], v[18:33]
	ds_read_b64_tr_b16 v[42:43], v49 offset:64
	ds_read_b64_tr_b16 v[44:45], v49 offset:576
	s_waitcnt lgkmcnt(0)
	v_mfma_f32_32x32x16_bf16 v[2:17], v[42:45], v[38:41], v[2:17]
	v_or_b32_e32 v42, 64, v46
	v_lshl_add_u32 v40, v42, 8, v47
	v_lshlrev_b32_e32 v42, 7, v42
	v_add3_u32 v49, v37, v42, v48
	ds_read_b64_tr_b16 v[38:39], v40 offset:32768
	ds_read_b64_tr_b16 v[40:41], v40 offset:33792
	ds_read_b64_tr_b16 v[42:43], v49
	ds_read_b64_tr_b16 v[44:45], v49 offset:512
	s_waitcnt lgkmcnt(0)
	v_mfma_f32_32x32x16_bf16 v[18:33], v[42:45], v[38:41], v[18:33]
	ds_read_b64_tr_b16 v[42:43], v49 offset:64
	ds_read_b64_tr_b16 v[44:45], v49 offset:576
	s_waitcnt lgkmcnt(0)
	v_mfma_f32_32x32x16_bf16 v[2:17], v[42:45], v[38:41], v[2:17]
	v_or_b32_e32 v42, 0x50, v46
	v_lshl_add_u32 v40, v42, 8, v47
	v_lshlrev_b32_e32 v42, 7, v42
	v_add3_u32 v49, v37, v42, v48
	ds_read_b64_tr_b16 v[38:39], v40 offset:32768
	ds_read_b64_tr_b16 v[40:41], v40 offset:33792
	ds_read_b64_tr_b16 v[42:43], v49
	ds_read_b64_tr_b16 v[44:45], v49 offset:512
	s_waitcnt lgkmcnt(0)
	v_mfma_f32_32x32x16_bf16 v[18:33], v[42:45], v[38:41], v[18:33]
	ds_read_b64_tr_b16 v[42:43], v49 offset:64
	ds_read_b64_tr_b16 v[44:45], v49 offset:576
	s_waitcnt lgkmcnt(0)
	v_mfma_f32_32x32x16_bf16 v[2:17], v[42:45], v[38:41], v[2:17]
	v_or_b32_e32 v42, 0x60, v46
	v_lshl_add_u32 v40, v42, 8, v47
	v_lshlrev_b32_e32 v42, 7, v42
	v_add3_u32 v49, v37, v42, v48
	ds_read_b64_tr_b16 v[38:39], v40 offset:32768
	ds_read_b64_tr_b16 v[40:41], v40 offset:33792
	ds_read_b64_tr_b16 v[42:43], v49
	ds_read_b64_tr_b16 v[44:45], v49 offset:512
	s_waitcnt lgkmcnt(0)
	v_mfma_f32_32x32x16_bf16 v[18:33], v[42:45], v[38:41], v[18:33]
	ds_read_b64_tr_b16 v[42:43], v49 offset:64
	ds_read_b64_tr_b16 v[44:45], v49 offset:576
	s_waitcnt lgkmcnt(0)
	v_mfma_f32_32x32x16_bf16 v[2:17], v[42:45], v[38:41], v[2:17]
	v_or_b32_e32 v42, 0x70, v46
	v_lshl_add_u32 v40, v42, 8, v47
	v_lshlrev_b32_e32 v42, 7, v42
	v_add3_u32 v37, v37, v42, v48
	ds_read_b64_tr_b16 v[38:39], v40 offset:32768
	ds_read_b64_tr_b16 v[40:41], v40 offset:33792
	ds_read_b64_tr_b16 v[42:43], v37
	ds_read_b64_tr_b16 v[44:45], v37 offset:512
	s_waitcnt lgkmcnt(0)
	v_mfma_f32_32x32x16_bf16 v[18:33], v[42:45], v[38:41], v[18:33]
	ds_read_b64_tr_b16 v[42:43], v37 offset:64
	ds_read_b64_tr_b16 v[44:45], v37 offset:576
	v_and_b32_e32 v37, 31, v35
	v_ashrrev_i32_e32 v35, 31, v34
	v_lshlrev_b64 v[34:35], 14, v[34:35]
	v_or3_b32 v0, v36, v37, v0
	v_lshl_add_u64 v[34:35], s[6:7], 0, v[34:35]
	v_lshlrev_b32_e32 v0, 1, v0
	v_lshl_add_u64 v[34:35], v[34:35], 0, v[0:1]
	s_nop 2
	v_cvt_pk_bf16_f32 v0, v19, s0
	global_store_short v[34:35], v0, off offset:256
	v_cvt_pk_bf16_f32 v0, v20, s0
	global_store_short v[34:35], v0, off offset:512
	v_cvt_pk_bf16_f32 v0, v21, s0
	v_cvt_pk_bf16_f32 v18, v18, s0
	global_store_short v[34:35], v0, off offset:768
	v_cvt_pk_bf16_f32 v0, v22, s0
	s_movk_i32 s6, 0x1000
	global_store_short v[34:35], v18, off
	global_store_short v[34:35], v0, off offset:2048
	v_cvt_pk_bf16_f32 v0, v23, s0
	v_add_co_u32_e32 v18, vcc, s6, v34
	global_store_short v[34:35], v0, off offset:2304
	v_cvt_pk_bf16_f32 v0, v24, s0
	v_addc_co_u32_e32 v19, vcc, 0, v35, vcc
	global_store_short v[34:35], v0, off offset:2560
	v_cvt_pk_bf16_f32 v0, v25, s0
	v_add_co_u32_e32 v20, vcc, s94, v34
	s_waitcnt lgkmcnt(0)
	v_mfma_f32_32x32x16_bf16 v[2:17], v[42:45], v[38:41], v[2:17]
	global_store_short v[34:35], v0, off offset:2816
	v_cvt_pk_bf16_f32 v0, v26, s0
	v_addc_co_u32_e32 v21, vcc, 0, v35, vcc
	global_store_short v[20:21], v0, off offset:-4096
	v_cvt_pk_bf16_f32 v0, v27, s0
	global_store_short v[18:19], v0, off offset:256
	v_cvt_pk_bf16_f32 v0, v28, s0
	global_store_short v[18:19], v0, off offset:512
	v_cvt_pk_bf16_f32 v0, v29, s0
	global_store_short v[18:19], v0, off offset:768
	v_cvt_pk_bf16_f32 v0, v30, s0
	global_store_short v[18:19], v0, off offset:2048
	v_cvt_pk_bf16_f32 v0, v31, s0
	global_store_short v[18:19], v0, off offset:2304
	v_cvt_pk_bf16_f32 v0, v32, s0
	global_store_short v[18:19], v0, off offset:2560
	v_cvt_pk_bf16_f32 v0, v33, s0
	global_store_short v[18:19], v0, off offset:2816
	v_cvt_pk_bf16_f32 v0, v2, s0
	global_store_short v[20:21], v0, off
	v_cvt_pk_bf16_f32 v0, v3, s0
	global_store_short v[20:21], v0, off offset:256
	v_cvt_pk_bf16_f32 v0, v4, s0
	global_store_short v[20:21], v0, off offset:512
	v_cvt_pk_bf16_f32 v0, v5, s0
	global_store_short v[20:21], v0, off offset:768
	v_cvt_pk_bf16_f32 v0, v6, s0
	global_store_short v[20:21], v0, off offset:2048
	v_cvt_pk_bf16_f32 v0, v7, s0
	global_store_short v[20:21], v0, off offset:2304
	v_cvt_pk_bf16_f32 v0, v8, s0
	s_movk_i32 s6, 0x3000
	global_store_short v[20:21], v0, off offset:2560
	v_cvt_pk_bf16_f32 v0, v9, s0
	v_add_co_u32_e32 v2, vcc, s6, v34
	global_store_short v[20:21], v0, off offset:2816
	v_cvt_pk_bf16_f32 v0, v10, s0
	v_addc_co_u32_e32 v3, vcc, 0, v35, vcc
	global_store_short v[2:3], v0, off
	v_cvt_pk_bf16_f32 v0, v11, s0
	global_store_short v[2:3], v0, off offset:256
	v_cvt_pk_bf16_f32 v0, v12, s0
	global_store_short v[2:3], v0, off offset:512
	v_cvt_pk_bf16_f32 v0, v13, s0
	global_store_short v[2:3], v0, off offset:768
	v_cvt_pk_bf16_f32 v0, v14, s0
	global_store_short v[2:3], v0, off offset:2048
	v_cvt_pk_bf16_f32 v0, v15, s0
	global_store_short v[2:3], v0, off offset:2304
	v_cvt_pk_bf16_f32 v0, v16, s0
	global_store_short v[2:3], v0, off offset:2560
	v_cvt_pk_bf16_f32 v0, v17, s0
	global_store_short v[2:3], v0, off offset:2816
	s_barrier
	s_cbranch_scc0 .LBB0_333

.LBB0_519:
	s_lshl_b32 s0, s28, 26
	s_add_u32 s0, s18, s0
	s_addc_u32 s1, s19, 0
	s_add_u32 s0, s0, 0x3c00000
	v_lshrrev_b32_e32 v17, 1, v13
	s_addc_u32 s1, s1, 0
	v_and_b32_e32 v17, 24, v17
	s_add_u32 s40, s18, 0x19c00000
	v_and_b32_e32 v16, 15, v13
	v_lshlrev_b32_e32 v18, 1, v17
	v_lshlrev_b32_e32 v13, 2, v13
	s_addc_u32 s41, s19, 0
	s_and_b32 s6, s20, 3
	v_lshl_or_b32 v179, s21, 6, v16
	v_lshl_or_b32 v16, v16, 6, v18
	s_lshl_b32 s7, s21, 13
	v_and_b32_e32 v13, 32, v13
	v_bitop3_b32 v18, v16, s7, v13 bitop3:0xde
	s_lshl_b32 s7, s6, 12
	s_add_i32 m0, s3, 0x18000
	v_lshl_add_u64 v[8:9], v[8:9], 0, s[24:25]
	v_bitop3_b32 v184, v16, s7, v13 bitop3:0xde
	s_waitcnt vmcnt(4)
	s_barrier
	global_load_lds_dwordx4 v[8:9], off
	v_lshl_add_u64 v[6:7], v[6:7], 0, s[24:25]
	s_add_i32 m0, s3, 0x1a000
	s_add_i32 s7, s3, 0x8000
	s_add_i32 s18, s3, 0xa000
	global_load_lds_dwordx4 v[6:7], off
	v_lshl_add_u64 v[4:5], v[4:5], 0, s[24:25]
	s_mov_b32 m0, s7
	s_add_u32 s20, s90, 0x20080
	global_load_lds_dwordx4 v[4:5], off
	v_lshl_add_u64 v[2:3], v[2:3], 0, s[24:25]
	s_mov_b32 m0, s18
	s_addc_u32 s21, s91, 0
	global_load_lds_dwordx4 v[2:3], off
	s_add_i32 m0, s3, 0x1c000
	v_lshl_add_u64 v[2:3], s[20:21], 0, v[162:163]
	global_load_lds_dwordx4 v[2:3], off
	v_lshl_add_u64 v[2:3], s[20:21], 0, v[164:165]
	s_add_i32 m0, s3, 0x1e000
	v_or_b32_e32 v186, 16, v179
	global_load_lds_dwordx4 v[2:3], off
	v_lshlrev_b32_e32 v2, 8, v179
	v_and_b32_e32 v185, 0xcf00, v2
	v_lshlrev_b32_e32 v2, 8, v186
	v_or_b32_e32 v188, 32, v179
	v_and_b32_e32 v187, 0xdf00, v2
	v_lshlrev_b32_e32 v2, 8, v188
	v_or_b32_e32 v190, 48, v179
	v_and_b32_e32 v189, 0xef00, v2
	v_lshlrev_b32_e32 v2, 8, v190
	v_add_u32_e32 v192, 0x80, v179
	v_and_b32_e32 v191, 0xff00, v2
	v_lshlrev_b32_e32 v2, 8, v192
	v_add_u32_e32 v194, 0x90, v179
	v_and_b32_e32 v193, 0xcf00, v2
	v_lshlrev_b32_e32 v2, 8, v194
	v_add_u32_e32 v196, 0xa0, v179
	v_and_b32_e32 v195, 0xdf00, v2
	v_lshlrev_b32_e32 v2, 8, v196
	v_add_u32_e32 v198, 0xb0, v179
	v_and_b32_e32 v197, 0xef00, v2
	v_lshlrev_b32_e32 v2, 8, v198
	v_and_b32_e32 v199, 0xff00, v2
	v_lshlrev_b32_e32 v2, 13, v0
	v_and_b32_e32 v2, 0xffffc000, v2
	v_lshl_add_u32 v2, v10, 10, v2
	v_and_b32_e32 v0, 1, v0
	v_lshl_or_b32 v0, v0, 6, v2
	v_lshl_add_u32 v166, v11, 1, v0
	v_lshlrev_b32_e32 v0, 13, v12
	v_and_b32_e32 v0, 0xffffc000, v0
	s_waitcnt vmcnt(6)
	v_lshl_add_u32 v0, v14, 10, v0
	v_and_b32_e32 v2, 1, v12
	v_lshl_or_b32 v0, v2, 6, v0
	s_ashr_i32 s19, s8, 31
	v_lshl_or_b32 v200, s6, 6, v17
	v_mov_b32_e32 v167, v1
	v_lshl_add_u32 v168, v15, 1, v0
	v_mov_b32_e32 v169, v1
	s_mov_b32 s20, 0
	v_add_u32_e32 v201, 0, v18
	s_barrier
	s_branch .LBB0_521
	s_nop 0
	s_nop 0
.LBB0_520:
	s_waitcnt vmcnt(0)
	v_lshlrev_b32_e32 v68, 16, v62
	v_and_b32_e32 v69, 0xffff0000, v62
	v_lshlrev_b32_e32 v62, 16, v63
	v_and_b32_e32 v63, 0xffff0000, v63
	v_pk_mul_f32 v[68:69], v[174:175], v[68:69]
	v_lshlrev_b32_e32 v70, 16, v58
	v_and_b32_e32 v71, 0xffff0000, v58
	v_pk_mul_f32 v[62:63], v[174:175], v[62:63]
	v_lshlrev_b32_e32 v58, 16, v59
	v_and_b32_e32 v59, 0xffff0000, v59
	v_pk_fma_f32 v[30:31], v[30:31], v[70:71], v[68:69]
	v_pk_fma_f32 v[32:33], v[32:33], v[58:59], v[62:63]
	v_cvt_pk_bf16_f32 v30, v30, v31
	v_cvt_pk_bf16_f32 v31, v32, v33
	v_lshlrev_b32_e32 v32, 16, v64
	v_and_b32_e32 v33, 0xffff0000, v64
	v_pk_mul_f32 v[32:33], v[174:175], v[32:33]
	v_lshlrev_b32_e32 v58, 16, v60
	v_and_b32_e32 v59, 0xffff0000, v60
	v_pk_fma_f32 v[26:27], v[26:27], v[58:59], v[32:33]
	v_lshlrev_b32_e32 v58, 16, v61
	v_cvt_pk_bf16_f32 v32, v26, v27
	v_lshlrev_b32_e32 v26, 16, v65
	v_and_b32_e32 v27, 0xffff0000, v65
	v_pk_mul_f32 v[26:27], v[174:175], v[26:27]
	v_and_b32_e32 v59, 0xffff0000, v61
	v_pk_fma_f32 v[26:27], v[28:29], v[58:59], v[26:27]
	v_lshlrev_b32_e32 v28, 16, v46
	v_cvt_pk_bf16_f32 v33, v26, v27
	v_lshlrev_b32_e32 v26, 16, v50
	v_and_b32_e32 v27, 0xffff0000, v50
	v_pk_mul_f32 v[26:27], v[174:175], v[26:27]
	v_and_b32_e32 v29, 0xffff0000, v46
	v_pk_fma_f32 v[22:23], v[22:23], v[28:29], v[26:27]
	v_lshlrev_b32_e32 v26, 16, v51
	v_and_b32_e32 v27, 0xffff0000, v51
	v_pk_mul_f32 v[26:27], v[174:175], v[26:27]
	v_lshlrev_b32_e32 v28, 16, v47
	v_and_b32_e32 v29, 0xffff0000, v47
	v_pk_fma_f32 v[24:25], v[24:25], v[28:29], v[26:27]
	v_cvt_pk_bf16_f32 v22, v22, v23
	v_cvt_pk_bf16_f32 v23, v24, v25
	v_lshlrev_b32_e32 v24, 16, v52
	v_and_b32_e32 v25, 0xffff0000, v52
	v_pk_mul_f32 v[24:25], v[174:175], v[24:25]
	v_lshlrev_b32_e32 v26, 16, v48
	v_and_b32_e32 v27, 0xffff0000, v48
	v_add_u32_e32 v66, 0xa0, v170
	v_pk_fma_f32 v[18:19], v[18:19], v[26:27], v[24:25]
	v_ashrrev_i32_e32 v67, 31, v66
	v_cvt_pk_bf16_f32 v24, v18, v19
	v_lshlrev_b32_e32 v18, 16, v53
	v_and_b32_e32 v19, 0xffff0000, v53
	v_lshlrev_b64 v[66:67], 11, v[66:67]
	v_pk_mul_f32 v[18:19], v[174:175], v[18:19]
	v_lshlrev_b32_e32 v26, 16, v49
	v_and_b32_e32 v27, 0xffff0000, v49
	v_lshl_add_u64 v[66:67], s[0:1], 0, v[66:67]
	v_mov_b32_e32 v173, v1
	v_pk_fma_f32 v[18:19], v[20:21], v[26:27], v[18:19]
	v_lshl_add_u64 v[66:67], v[66:67], 0, v[172:173]
	v_cvt_pk_bf16_f32 v25, v18, v19
	v_lshlrev_b32_e32 v20, 16, v54
	v_and_b32_e32 v21, 0xffff0000, v54
	global_store_dwordx4 v[66:67], v[22:25], off offset:64
	v_pk_mul_f32 v[20:21], v[174:175], v[20:21]
	v_add_u32_e32 v18, 0xb0, v170
	v_lshlrev_b32_e32 v22, 16, v42
	v_and_b32_e32 v23, 0xffff0000, v42
	v_pk_fma_f32 v[14:15], v[14:15], v[22:23], v[20:21]
	v_lshlrev_b32_e32 v20, 16, v55
	v_and_b32_e32 v21, 0xffff0000, v55
	v_pk_mul_f32 v[20:21], v[174:175], v[20:21]
	v_lshlrev_b32_e32 v22, 16, v43
	v_and_b32_e32 v23, 0xffff0000, v43
	v_pk_fma_f32 v[16:17], v[16:17], v[22:23], v[20:21]
	v_cvt_pk_bf16_f32 v14, v14, v15
	v_cvt_pk_bf16_f32 v15, v16, v17
	v_lshlrev_b32_e32 v16, 16, v56
	v_and_b32_e32 v17, 0xffff0000, v56
	v_pk_mul_f32 v[16:17], v[174:175], v[16:17]
	v_lshlrev_b32_e32 v20, 16, v44
	v_and_b32_e32 v21, 0xffff0000, v44
	v_pk_fma_f32 v[10:11], v[10:11], v[20:21], v[16:17]
	v_lshlrev_b32_e32 v20, 16, v45
	v_cvt_pk_bf16_f32 v16, v10, v11
	v_lshlrev_b32_e32 v10, 16, v57
	v_and_b32_e32 v11, 0xffff0000, v57
	v_pk_mul_f32 v[10:11], v[174:175], v[10:11]
	v_and_b32_e32 v21, 0xffff0000, v45
	v_pk_fma_f32 v[10:11], v[12:13], v[20:21], v[10:11]
	v_lshlrev_b32_e32 v12, 16, v38
	v_cvt_pk_bf16_f32 v17, v10, v11
	v_lshlrev_b32_e32 v10, 16, v34
	v_and_b32_e32 v11, 0xffff0000, v34
	v_pk_mul_f32 v[10:11], v[174:175], v[10:11]
	v_and_b32_e32 v13, 0xffff0000, v38
	v_pk_fma_f32 v[6:7], v[6:7], v[12:13], v[10:11]
	v_lshlrev_b32_e32 v10, 16, v35
	v_and_b32_e32 v11, 0xffff0000, v35
	v_pk_mul_f32 v[10:11], v[174:175], v[10:11]
	v_lshlrev_b32_e32 v12, 16, v39
	v_and_b32_e32 v13, 0xffff0000, v39
	v_pk_fma_f32 v[8:9], v[8:9], v[12:13], v[10:11]
	v_cvt_pk_bf16_f32 v6, v6, v7
	v_cvt_pk_bf16_f32 v7, v8, v9
	v_lshlrev_b32_e32 v8, 16, v36
	v_and_b32_e32 v9, 0xffff0000, v36
	v_pk_mul_f32 v[8:9], v[174:175], v[8:9]
	v_lshlrev_b32_e32 v10, 16, v40
	v_and_b32_e32 v11, 0xffff0000, v40
	v_pk_fma_f32 v[2:3], v[2:3], v[10:11], v[8:9]
	v_ashrrev_i32_e32 v19, 31, v18
	v_cvt_pk_bf16_f32 v8, v2, v3
	v_lshlrev_b32_e32 v2, 16, v37
	v_and_b32_e32 v3, 0xffff0000, v37
	v_lshlrev_b64 v[18:19], 11, v[18:19]
	v_pk_mul_f32 v[2:3], v[174:175], v[2:3]
	v_lshlrev_b32_e32 v10, 16, v41
	v_and_b32_e32 v11, 0xffff0000, v41
	v_lshl_add_u64 v[18:19], s[0:1], 0, v[18:19]
	v_pk_fma_f32 v[2:3], v[4:5], v[10:11], v[2:3]
	v_lshl_add_u64 v[18:19], v[18:19], 0, v[172:173]
	v_cvt_pk_bf16_f32 v9, v2, v3
	s_and_b64 vcc, exec, s[36:37]
	s_mov_b32 s38, s68
	s_mov_b32 s2, s46
	s_mov_b64 s[90:91], s[88:89]
	s_mov_b64 s[62:63], s[84:85]
	global_store_dwordx4 v[66:67], v[30:33], off
	global_store_dwordx4 v[18:19], v[14:17], off
	global_store_dwordx4 v[18:19], v[6:9], off offset:64
	s_cbranch_vccnz .LBB0_545
